# P0 weight conversion loop: gain loads issued before next-tile loads; wait for next tile only after current tile is transposed+stored
# baseline (speedup 1.0000x reference)
; __device__ __forceinline__ TrItem tr_decode(int it, const float* const* in, unsigned char* ws, int lane) {
;     int r = it, kind = 0, ndb = 32, N = D, K = D; const float *W, *W2 = nullptr, *gain = nullptr; bf16_t* WT; bool nts = false, woh = false;
;     if (r < 5632) { kind = 1; W = in[3]; W2 = in[4]; N = FF; ndb = 176; gain = in[2]; WT = (bf16_t*)(ws + WS_W1GU); }
;     else if ((r -= 5632) < 2816) { W = in[5]; K = FF; WT = (bf16_t*)(ws + WS_W1D); }
;     else if ((r -= 2816) < 2688) { kind = 2; W = in[7]; N = INC; ndb = 84; gain = in[6]; WT = (bf16_t*)(ws + WS_WIN); nts = true; }
;     else if ((r -= 2688) < 1024) { W = in[10]; WT = (bf16_t*)(ws + WS_WOUT); nts = true; }
;     else if ((r -= 1024) < 1024) { W = in[13]; gain = in[11]; WT = (bf16_t*)(ws + WS_WQ); nts = true; }
;     else if ((r -= 1024) < 2048) { W = in[14]; N = 2 * D; ndb = 64; gain = in[12]; WT = (bf16_t*)(ws + WS_WKV); }
;     else if ((r -= 2048) < 1024) { W = in[15]; WT = (bf16_t*)(ws + WS_WO); nts = true; woh = true; }
;     else if ((r -= 1024) < 5632) { kind = 1; W = in[17]; W2 = in[18]; N = FF; ndb = 176; gain = in[16]; WT = (bf16_t*)(ws + WS_W2GU); nts = true; }
;     else { r -= 5632; W = in[19]; K = FF; WT = (bf16_t*)(ws + WS_W2D); }
; __device__ __forceinline__ void tr_all(const float* const* in, unsigned char* ws, LAS float* scr, int gw, int ngw, int lane, const TrRanges rg) {
;     ...
;         if (cur.gain) { g0 = *(const f32x4*)cur.gain; g1 = *(const f32x4*)(cur.gain + 4); }
.LBB0_217:
	v_cmp_ne_u64_e32 vcc, 0, v[146:147]
	v_mov_b32_e32 v192, 1.0
	v_mov_b32_e32 v193, 1.0
	v_mov_b32_e32 v194, 1.0
	v_mov_b32_e32 v195, 1.0
	v_mov_b32_e32 v196, 1.0
	v_mov_b32_e32 v197, 1.0
	v_mov_b32_e32 v198, 1.0
	v_mov_b32_e32 v199, 1.0
	s_and_saveexec_b64 s[100:101], vcc
	s_cbranch_execz .Ltr_g_i2
	global_load_dwordx4 v[192:195], v[146:147], off
	global_load_dwordx4 v[196:199], v[146:147], off offset:16
.Ltr_g_i2:
	s_or_b64 exec, exec, s[100:101]
	s_add_i32 s5, s18, s2
	s_cmpk_lt_i32 s5, 0x1c00
	s_cselect_b64 s[16:17], -1, 0
	s_cmpk_gt_i32 s5, 0x1bff
	s_cselect_b64 s[14:15], -1, 0
	s_and_b64 vcc, exec, s[14:15]
	v_mov_b64_e32 v[148:149], v[146:147]
	v_mov_b64_e32 v[150:151], v[142:143]
	s_mov_b32 s33, s0
	s_cbranch_vccnz .LBB0_266
	s_cmpk_lt_i32 s5, 0x1000
	s_movk_i32 s19, 0x4580
	s_cselect_b32 s19, s19, 0x2380
	s_add_i32 s26, s2, s19
	s_add_i32 s42, s19, s5
	s_add_i32 s26, s26, s18
	s_cmpk_lt_i32 s26, 0x1600
	s_mov_b64 s[28:29], -1
	s_cbranch_scc1 .LBB0_228
	s_cmpk_gt_u32 s26, 0x20ff
	s_cbranch_scc0 .LBB0_229
	s_cmpk_gt_u32 s26, 0x2b7f
	s_cbranch_scc0 .LBB0_230
	s_cmpk_gt_u32 s26, 0x2f7f
	s_cbranch_scc0 .LBB0_231
	s_cmpk_gt_u32 s26, 0x337f
	s_cbranch_scc0 .LBB0_232
	s_cmpk_gt_u32 s26, 0x3b7f
	s_cbranch_scc0 .LBB0_233
	v_readlane_b32 s48, v254, 18
	v_readlane_b32 s62, v254, 32
	v_readlane_b32 s63, v254, 33
	s_cmpk_gt_u32 s26, 0x3f7f
	s_mov_b64 s[34:35], -1
	s_mov_b64 s[18:19], s[62:63]
	s_mov_b64 s[20:21], -1
	v_readlane_b32 s49, v254, 19
	v_readlane_b32 s50, v254, 20
	v_readlane_b32 s51, v254, 21
	v_readlane_b32 s52, v254, 22
	v_readlane_b32 s53, v254, 23
	v_readlane_b32 s54, v254, 24
	v_readlane_b32 s55, v254, 25
	v_readlane_b32 s56, v254, 26
	v_readlane_b32 s57, v254, 27
	v_readlane_b32 s58, v254, 28
	v_readlane_b32 s59, v254, 29
	v_readlane_b32 s60, v254, 30
	v_readlane_b32 s61, v254, 31
	s_cbranch_scc0 .LBB0_226
	v_readlane_b32 s48, v254, 4
	v_readlane_b32 s49, v254, 5
	v_readlane_b32 s50, v254, 6
	v_readlane_b32 s51, v254, 7
	v_readlane_b32 s52, v254, 8
	v_readlane_b32 s53, v254, 9
	s_add_i32 s44, s26, 0xffffc080
	s_mov_b64 s[20:21], 0
	v_readlane_b32 s54, v254, 10
	v_readlane_b32 s55, v254, 11
	s_mov_b64 s[18:19], s[50:51]
	s_mov_b64 s[24:25], s[52:53]
	s_mov_b64 s[22:23], s[48:49]

; #define LAS __attribute__((address_space(3)))
; #define TR_LOAD(p) __builtin_nontemporal_load(p)
; __device__ __forceinline__ TrItem tr_decode(int it, const float* const* in, unsigned char* ws, int lane) {
;     ...
;     const int blk = d0 + 32 * ((lane & 15) >> 3);
;     const float* src = W; int s0 = blk;
;     if (kind == 1) { const int pn = blk >> 8, bj = (blk >> 7) & 1, o = blk & 127; src = bj ? W2 : W; s0 = pn * 128 + o; }
;     else if (kind == 2) s0 = win_src(blk);
;     TrItem t; t.src = src + (size_t)(k0 + (lane >> 4)) * N + s0 + 4 * (lane & 7); t.gain = gain ? gain + k0 + 8 * (lane & 7) : nullptr;
;     t.dst = WT + (size_t)(d0 + (lane >> 3)) * K + k0 + 8 * (lane & 7); t.N = N; t.K = K; t.nts = nts && TR_NTS;
;     if (woh) { t.dst = WT + ((size_t)((k0 >> 9) * 2048 + d0 + (lane >> 3))) * 512 + (k0 & 511) + 8 * (lane & 7); t.K = 512; }
;     return t;
; }
;     __device__ __forceinline__ int count() const { return (e0 - b0) + (e1 - b1) + (e2 - b2); }
; __device__ __forceinline__ void tr_all(const float* const* in, unsigned char* ws, LAS float* scr, int gw, int ngw, int lane, const TrRanges rg) {
;     const int TR_CNT = rg.count();
;     if (gw >= TR_CNT) return;
;     TrItem cur = tr_decode(rg.item(gw), in, ws, lane);
;     f32x4 v[16];
; #pragma unroll
;     for (int i = 0; i < 16; ++i) v[i] = TR_LOAD((const f32x4*)(cur.src + (size_t)(4 * i) * cur.N));
;     for (int it = gw; it < TR_CNT; it += ngw) {
;         const int nit = it + ngw; const bool hn = nit < TR_CNT;
;         TrItem nx = cur; f32x4 w[16];
;         if (hn) { nx = tr_decode(rg.item(nit), in, ws, lane);
; #pragma unroll
;             for (int i = 0; i < 16; ++i) w[i] = TR_LOAD((const f32x4*)(nx.src + (size_t)(4 * i) * nx.N)); }
.LBB0_265:
	s_lshl_b64 s[26:27], s[24:25], 2
	s_add_u32 s26, s22, s26
	s_addc_u32 s27, s23, s27
	v_or_b32_e32 v67, s24, v153
	s_cmp_lg_u64 s[22:23], 0
	v_mul_lo_u32 v70, s21, v67
	s_mul_i32 s24, s20, s25
	v_mad_u64_u32 v[68:69], s[22:23], s20, v67, 0
	v_add3_u32 v69, v69, s24, v70
	v_lshl_add_u64 v[68:69], v[68:69], 2, s[18:19]
	v_ashrrev_i32_e32 v67, 31, v66
	v_lshl_add_u64 v[66:67], v[66:67], 2, v[68:69]
	v_mov_b32_e32 v145, v139
	s_cselect_b64 vcc, -1, 0
	v_lshl_add_u64 v[66:67], v[66:67], 0, v[144:145]
	s_lshl_b64 s[18:19], s[20:21], 4
	v_lshl_add_u64 v[74:75], v[66:67], 0, s[18:19]
	global_load_dwordx4 v[70:73], v[66:67], off nt
	s_nop 0
	global_load_dwordx4 v[66:69], v[74:75], off nt
	v_lshl_add_u64 v[74:75], v[74:75], 0, s[18:19]
	v_lshl_add_u64 v[82:83], v[74:75], 0, s[18:19]
	global_load_dwordx4 v[78:81], v[74:75], off nt
	s_nop 0
	global_load_dwordx4 v[74:77], v[82:83], off nt
	v_lshl_add_u64 v[82:83], v[82:83], 0, s[18:19]
	v_lshl_add_u64 v[90:91], v[82:83], 0, s[18:19]
	global_load_dwordx4 v[86:89], v[82:83], off nt
	s_nop 0
	global_load_dwordx4 v[82:85], v[90:91], off nt
	v_lshl_add_u64 v[90:91], v[90:91], 0, s[18:19]
	v_lshl_add_u64 v[98:99], v[90:91], 0, s[18:19]
	v_lshl_add_u64 v[102:103], v[98:99], 0, s[18:19]
	v_lshl_add_u64 v[106:107], v[102:103], 0, s[18:19]
	v_lshl_add_u64 v[110:111], v[106:107], 0, s[18:19]
	v_lshl_add_u64 v[114:115], v[110:111], 0, s[18:19]
	v_lshl_add_u64 v[118:119], v[114:115], 0, s[18:19]
	v_lshl_add_u64 v[122:123], v[118:119], 0, s[18:19]
	v_lshl_add_u64 v[126:127], v[122:123], 0, s[18:19]
	global_load_dwordx4 v[94:97], v[90:91], off nt
	s_nop 0
	global_load_dwordx4 v[90:93], v[98:99], off nt
	v_lshlrev_b32_e32 v138, 2, v140
	global_load_dwordx4 v[98:101], v[102:103], off nt
	v_lshl_add_u64 v[132:133], s[26:27], 0, v[138:139]
	global_load_dwordx4 v[102:105], v[106:107], off nt
	v_lshlrev_b32_e32 v138, 1, v140
	global_load_dwordx4 v[106:109], v[110:111], off nt
	v_cndmask_b32_e32 v149, 0, v133, vcc
	global_load_dwordx4 v[110:113], v[114:115], off nt
	v_cndmask_b32_e32 v148, 0, v132, vcc
	global_load_dwordx4 v[114:117], v[118:119], off nt
	v_lshl_add_u64 v[150:151], v[130:131], 0, v[138:139]
	global_load_dwordx4 v[118:121], v[122:123], off nt
	s_nop 0
	global_load_dwordx4 v[122:125], v[126:127], off nt
	v_lshl_add_u64 v[126:127], v[126:127], 0, s[18:19]
	global_load_dwordx4 v[126:129], v[126:127], off nt
	s_waitcnt vmcnt(16)
	s_branch .Ltr_w_i2

; #define LAS __attribute__((address_space(3)))
; __device__ __forceinline__ unsigned cvtpk(float lo, float hi) { f32x2_t v = {lo, hi}; bf16x2_t b = __builtin_convertvector(v, bf16x2_t); return __builtin_bit_cast(unsigned, b); }
; __device__ __forceinline__ void tr_all(const float* const* in, unsigned char* ws, LAS float* scr, int gw, int ngw, int lane, const TrRanges rg) {
;     ...
;         LAS float* wp = scr + (lane >> 4) * 65 + 4 * (lane & 15);
; #pragma unroll
;         for (int i = 0; i < 16; ++i) { wp[(4 * i) * 65 + 0] = v[i][0]; wp[(4 * i) * 65 + 1] = v[i][1]; wp[(4 * i) * 65 + 2] = v[i][2]; wp[(4 * i) * 65 + 3] = v[i][3]; }
;         f32x4 g0 = {1.f, 1.f, 1.f, 1.f}, g1 = {1.f, 1.f, 1.f, 1.f};
;         if (cur.gain) { g0 = *(const f32x4*)cur.gain; g1 = *(const f32x4*)(cur.gain + 4); }
;         asm volatile("s_waitcnt lgkmcnt(0)" ::: "memory");
;         const LAS float* rp = scr + (8 * (lane & 7)) * 65 + (lane >> 3);
; #pragma unroll
;         for (int j = 0; j < 8; ++j) { const LAS float* s = rp + 8 * j;
;             u32x4 o; o.x = cvtpk(s[0 * 65] * g0[0], s[1 * 65] * g0[1]); o.y = cvtpk(s[2 * 65] * g0[2], s[3 * 65] * g0[3]);
;             o.z = cvtpk(s[4 * 65] * g1[0], s[5 * 65] * g1[1]); o.w = cvtpk(s[6 * 65] * g1[2], s[7 * 65] * g1[3]);
;             if (cur.nts) __builtin_nontemporal_store(o, (u32x4*)(cur.dst + (size_t)(8 * j) * cur.K)); else *(u32x4*)(cur.dst + (size_t)(8 * j) * cur.K) = o; }
.Ltr_w_i2:
	v_add_u32_e32 v130, 0x410, v154
	ds_write2_b32 v154, v62, v63 offset1:1
	ds_write2_b32 v154, v64, v65 offset0:2 offset1:3
	ds_write2_b32 v130, v58, v59 offset1:1
	v_add_u32_e32 v130, 0x418, v154
	ds_write2_b32 v130, v60, v61 offset1:1
	v_add_u32_e32 v130, 0x820, v154
	ds_write2_b32 v130, v54, v55 offset1:1
	v_add_u32_e32 v130, 0x828, v154
	ds_write2_b32 v130, v56, v57 offset1:1
	v_add_u32_e32 v130, 0xc30, v154
	ds_write2_b32 v130, v50, v51 offset1:1
	v_add_u32_e32 v130, 0xc38, v154
	ds_write2_b32 v130, v52, v53 offset1:1
	v_add_u32_e32 v130, 0x1040, v154
	ds_write2_b32 v130, v46, v47 offset1:1
	v_add_u32_e32 v130, 0x1048, v154
	ds_write2_b32 v130, v48, v49 offset1:1
	v_add_u32_e32 v130, 0x1450, v154
	ds_write2_b32 v130, v42, v43 offset1:1
	v_add_u32_e32 v130, 0x1458, v154
	ds_write2_b32 v130, v44, v45 offset1:1
	v_add_u32_e32 v130, 0x1860, v154
	ds_write2_b32 v130, v34, v35 offset1:1
	v_add_u32_e32 v130, 0x1868, v154
	ds_write2_b32 v130, v36, v37 offset1:1
	v_add_u32_e32 v130, 0x1c70, v154
	ds_write2_b32 v130, v30, v31 offset1:1
	v_add_u32_e32 v130, 0x1c78, v154
	ds_write2_b32 v130, v32, v33 offset1:1
	v_add_u32_e32 v130, 0x2080, v154
	ds_write2_b32 v130, v26, v27 offset1:1
	v_add_u32_e32 v130, 0x2088, v154
	ds_write2_b32 v130, v28, v29 offset1:1
	v_add_u32_e32 v130, 0x2490, v154
	ds_write2_b32 v130, v22, v23 offset1:1
	v_add_u32_e32 v130, 0x2498, v154
	ds_write2_b32 v130, v24, v25 offset1:1
	v_add_u32_e32 v130, 0x28a0, v154
	ds_write2_b32 v130, v18, v19 offset1:1
	v_add_u32_e32 v130, 0x28a8, v154
	ds_write2_b32 v130, v20, v21 offset1:1
	v_add_u32_e32 v130, 0x2cb0, v154
	ds_write2_b32 v130, v14, v15 offset1:1
	v_add_u32_e32 v130, 0x2cb8, v154
	ds_write2_b32 v130, v16, v17 offset1:1
	v_add_u32_e32 v130, 0x30c0, v154
	ds_write2_b32 v130, v10, v11 offset1:1
	v_add_u32_e32 v130, 0x30c8, v154
	ds_write2_b32 v130, v12, v13 offset1:1
	v_add_u32_e32 v130, 0x34d0, v154
	ds_write2_b32 v130, v6, v7 offset1:1
	v_add_u32_e32 v130, 0x34d8, v154
	ds_write2_b32 v130, v8, v9 offset1:1
	v_add_u32_e32 v130, 0x38e0, v154
	ds_write2_b32 v130, v2, v3 offset1:1
	v_add_u32_e32 v130, 0x38e8, v154
	ds_write2_b32 v130, v4, v5 offset1:1
	v_add_u32_e32 v130, 0x3cf0, v154
	ds_write2_b32 v130, v38, v39 offset1:1
	v_add_u32_e32 v130, 0x3cf8, v154
	ds_write2_b32 v130, v40, v41 offset1:1
.LBB0_268:
	s_waitcnt lgkmcnt(0)
	ds_read2_b32 v[160:161], v155 offset1:8
	ds_read2_b32 v[162:163], v155 offset0:65 offset1:73
	ds_read2_b32 v[164:165], v155 offset0:130 offset1:138
	ds_read2_b32 v[166:167], v155 offset0:195 offset1:203
	v_add_u32_e32 v138, 0x400, v155
	ds_read2_b32 v[168:169], v138 offset0:4 offset1:12
	ds_read2_b32 v[170:171], v138 offset0:69 offset1:77
	ds_read2_b32 v[172:173], v138 offset0:134 offset1:142
	ds_read2_b32 v[174:175], v138 offset0:199 offset1:207
	s_waitcnt lgkmcnt(7)
	v_mov_b32_e32 v156, v160
	s_waitcnt lgkmcnt(6)
	v_mov_b32_e32 v157, v162
	s_waitcnt lgkmcnt(5)
	v_mov_b32_e32 v158, v164
	s_waitcnt lgkmcnt(4)
	v_mov_b32_e32 v159, v166
	v_pk_mul_f32 v[156:157], v[192:193], v[156:157]
	v_pk_mul_f32 v[158:159], v[194:195], v[158:159]
	v_cvt_pk_bf16_f32 v156, v156, v157
	v_cvt_pk_bf16_f32 v157, v158, v159
	s_waitcnt lgkmcnt(3)
	v_mov_b32_e32 v158, v168
	s_waitcnt lgkmcnt(2)
	v_mov_b32_e32 v159, v170
	s_waitcnt lgkmcnt(1)
	v_mov_b32_e32 v176, v172
	s_waitcnt lgkmcnt(0)
	v_mov_b32_e32 v177, v174
	v_pk_mul_f32 v[158:159], v[196:197], v[158:159]
	v_pk_mul_f32 v[176:177], v[198:199], v[176:177]
	v_cvt_pk_bf16_f32 v158, v158, v159
	v_cvt_pk_bf16_f32 v159, v176, v177
	v_mov_b32_e32 v162, v161
	v_mov_b32_e32 v166, v165
	global_store_dwordx4 v[142:143], v[156:159], off
	v_mov_b32_e32 v170, v169
	v_mov_b32_e32 v174, v173
	v_pk_mul_f32 v[156:157], v[192:193], v[162:163]
	v_pk_mul_f32 v[158:159], v[194:195], v[166:167]
	v_cvt_pk_bf16_f32 v156, v156, v157
	v_cvt_pk_bf16_f32 v157, v158, v159
	v_pk_mul_f32 v[158:159], v[196:197], v[170:171]
	v_pk_mul_f32 v[160:161], v[198:199], v[174:175]
	s_lshl_b64 s[18:19], s[0:1], 4
	v_cvt_pk_bf16_f32 v158, v158, v159
	v_cvt_pk_bf16_f32 v159, v160, v161
	ds_read2_b32 v[160:161], v155 offset0:16 offset1:24
	ds_read2_b32 v[162:163], v155 offset0:81 offset1:89
	v_lshl_add_u64 v[164:165], v[142:143], 0, s[18:19]
	ds_read2_b32 v[166:167], v155 offset0:146 offset1:154
	ds_read2_b32 v[168:169], v155 offset0:211 offset1:219
	global_store_dwordx4 v[164:165], v[156:159], off
	ds_read2_b32 v[170:171], v138 offset0:20 offset1:28
	ds_read2_b32 v[172:173], v138 offset0:85 offset1:93
	ds_read2_b32 v[174:175], v138 offset0:150 offset1:158
	ds_read2_b32 v[176:177], v138 offset0:215 offset1:223
	s_waitcnt lgkmcnt(7)
	v_mov_b32_e32 v156, v160
	s_waitcnt lgkmcnt(6)
	v_mov_b32_e32 v157, v162
	s_waitcnt lgkmcnt(5)
	v_mov_b32_e32 v158, v166
	s_waitcnt lgkmcnt(4)
	v_mov_b32_e32 v159, v168
	v_pk_mul_f32 v[156:157], v[192:193], v[156:157]
	v_pk_mul_f32 v[158:159], v[194:195], v[158:159]
	v_cvt_pk_bf16_f32 v156, v156, v157
	v_cvt_pk_bf16_f32 v157, v158, v159
	s_waitcnt lgkmcnt(3)
	v_mov_b32_e32 v158, v170
	s_waitcnt lgkmcnt(2)
	v_mov_b32_e32 v159, v172
	s_waitcnt lgkmcnt(1)
	v_mov_b32_e32 v178, v174
	s_waitcnt lgkmcnt(0)
; #define LAS __attribute__((address_space(3)))
; __device__ __forceinline__ unsigned cvtpk(float lo, float hi) { f32x2_t v = {lo, hi}; bf16x2_t b = __builtin_convertvector(v, bf16x2_t); return __builtin_bit_cast(unsigned, b); }
; __device__ __forceinline__ void tr_all(const float* const* in, unsigned char* ws, LAS float* scr, int gw, int ngw, int lane, const TrRanges rg) {
;     ...
;         for (int j = 0; j < 8; ++j) { const LAS float* s = rp + 8 * j;
;             u32x4 o; o.x = cvtpk(s[0 * 65] * g0[0], s[1 * 65] * g0[1]); o.y = cvtpk(s[2 * 65] * g0[2], s[3 * 65] * g0[3]);
;             o.z = cvtpk(s[4 * 65] * g1[0], s[5 * 65] * g1[1]); o.w = cvtpk(s[6 * 65] * g1[2], s[7 * 65] * g1[3]);
;             if (cur.nts) __builtin_nontemporal_store(o, (u32x4*)(cur.dst + (size_t)(8 * j) * cur.K)); else *(u32x4*)(cur.dst + (size_t)(8 * j) * cur.K) = o; }
;         asm volatile("s_waitcnt lgkmcnt(0)" ::: "memory");
;         if (hn) {
; #pragma unroll
;             for (int i = 0; i < 16; ++i) v[i] = w[i];
;             cur = nx; }
	v_mov_b32_e32 v179, v176
	v_pk_mul_f32 v[158:159], v[196:197], v[158:159]
	v_pk_mul_f32 v[178:179], v[198:199], v[178:179]
	v_cvt_pk_bf16_f32 v158, v158, v159
	v_cvt_pk_bf16_f32 v159, v178, v179
	v_lshl_add_u64 v[164:165], v[164:165], 0, s[18:19]
	v_mov_b32_e32 v162, v161
	v_mov_b32_e32 v168, v167
	global_store_dwordx4 v[164:165], v[156:159], off
	v_mov_b32_e32 v172, v171
	v_mov_b32_e32 v176, v175
	v_pk_mul_f32 v[156:157], v[192:193], v[162:163]
	v_pk_mul_f32 v[158:159], v[194:195], v[168:169]
	v_cvt_pk_bf16_f32 v156, v156, v157
	v_cvt_pk_bf16_f32 v157, v158, v159
	v_pk_mul_f32 v[158:159], v[196:197], v[172:173]
	v_pk_mul_f32 v[160:161], v[198:199], v[176:177]
	v_cvt_pk_bf16_f32 v158, v158, v159
	ds_read2_b32 v[162:163], v155 offset0:32 offset1:40
	v_cvt_pk_bf16_f32 v159, v160, v161
	ds_read2_b32 v[160:161], v155 offset0:97 offset1:105
	v_lshl_add_u64 v[164:165], v[164:165], 0, s[18:19]
	ds_read2_b32 v[166:167], v155 offset0:162 offset1:170
	ds_read2_b32 v[168:169], v155 offset0:227 offset1:235
	global_store_dwordx4 v[164:165], v[156:159], off
	ds_read2_b32 v[170:171], v138 offset0:36 offset1:44
	ds_read2_b32 v[172:173], v138 offset0:101 offset1:109
	ds_read2_b32 v[174:175], v138 offset0:166 offset1:174
	ds_read2_b32 v[176:177], v138 offset0:231 offset1:239
	s_waitcnt lgkmcnt(7)
	v_mov_b32_e32 v156, v162
	s_waitcnt lgkmcnt(6)
	v_mov_b32_e32 v157, v160
	s_waitcnt lgkmcnt(5)
	v_mov_b32_e32 v158, v166
	s_waitcnt lgkmcnt(4)
	v_mov_b32_e32 v159, v168
	v_pk_mul_f32 v[156:157], v[192:193], v[156:157]
	v_pk_mul_f32 v[158:159], v[194:195], v[158:159]
	v_cvt_pk_bf16_f32 v156, v156, v157
	v_cvt_pk_bf16_f32 v157, v158, v159
	s_waitcnt lgkmcnt(3)
	v_mov_b32_e32 v158, v170
	s_waitcnt lgkmcnt(2)
	v_mov_b32_e32 v159, v172
	s_waitcnt lgkmcnt(1)
	v_mov_b32_e32 v178, v174
	s_waitcnt lgkmcnt(0)
	v_mov_b32_e32 v179, v176
	v_pk_mul_f32 v[158:159], v[196:197], v[158:159]
	v_pk_mul_f32 v[178:179], v[198:199], v[178:179]
	v_cvt_pk_bf16_f32 v158, v158, v159
	v_cvt_pk_bf16_f32 v159, v178, v179
	v_lshl_add_u64 v[164:165], v[164:165], 0, s[18:19]
	v_mov_b32_e32 v160, v163
	v_mov_b32_e32 v168, v167
	global_store_dwordx4 v[164:165], v[156:159], off
	v_mov_b32_e32 v172, v171
	v_mov_b32_e32 v176, v175
	v_pk_mul_f32 v[156:157], v[192:193], v[160:161]
	v_pk_mul_f32 v[158:159], v[194:195], v[168:169]
	v_cvt_pk_bf16_f32 v156, v156, v157
	v_cvt_pk_bf16_f32 v157, v158, v159
	v_pk_mul_f32 v[158:159], v[196:197], v[172:173]
	v_pk_mul_f32 v[160:161], v[198:199], v[176:177]
	v_cvt_pk_bf16_f32 v158, v158, v159
	ds_read2_b32 v[162:163], v155 offset0:48 offset1:56
	v_cvt_pk_bf16_f32 v159, v160, v161
	ds_read2_b32 v[160:161], v155 offset0:113 offset1:121
	v_lshl_add_u64 v[164:165], v[164:165], 0, s[18:19]
	ds_read2_b32 v[166:167], v155 offset0:178 offset1:186
	ds_read2_b32 v[168:169], v155 offset0:243 offset1:251
	global_store_dwordx4 v[164:165], v[156:159], off
	ds_read2_b32 v[170:171], v138 offset0:52 offset1:60
	ds_read2_b32 v[172:173], v138 offset0:117 offset1:125
	ds_read2_b32 v[174:175], v138 offset0:182 offset1:190
	ds_read2_b32 v[176:177], v138 offset0:247 offset1:255
	s_waitcnt lgkmcnt(7)
	v_mov_b32_e32 v156, v162
	s_waitcnt lgkmcnt(6)
	v_mov_b32_e32 v157, v160
	s_waitcnt lgkmcnt(5)
	v_mov_b32_e32 v158, v166
	s_waitcnt lgkmcnt(4)
	v_mov_b32_e32 v159, v168
	v_pk_mul_f32 v[156:157], v[192:193], v[156:157]
	v_pk_mul_f32 v[158:159], v[194:195], v[158:159]
	v_mov_b32_e32 v160, v163
	v_mov_b32_e32 v168, v167
	v_cvt_pk_bf16_f32 v156, v156, v157
	v_cvt_pk_bf16_f32 v157, v158, v159
	s_waitcnt lgkmcnt(3)
	v_mov_b32_e32 v158, v170
	s_waitcnt lgkmcnt(2)
	v_mov_b32_e32 v159, v172
	s_waitcnt lgkmcnt(1)
	v_mov_b32_e32 v178, v174
	s_waitcnt lgkmcnt(0)
	v_mov_b32_e32 v179, v176
	v_pk_mul_f32 v[130:131], v[192:193], v[160:161]
	v_pk_mul_f32 v[132:133], v[194:195], v[168:169]
	v_mov_b32_e32 v172, v171
	v_mov_b32_e32 v176, v175
	v_pk_mul_f32 v[158:159], v[196:197], v[158:159]
	v_pk_mul_f32 v[178:179], v[198:199], v[178:179]
	v_lshl_add_u64 v[164:165], v[164:165], 0, s[18:19]
	v_cvt_pk_bf16_f32 v130, v130, v131
	v_cvt_pk_bf16_f32 v131, v132, v133
	v_pk_mul_f32 v[132:133], v[196:197], v[172:173]
	v_pk_mul_f32 v[134:135], v[198:199], v[176:177]
	v_cvt_pk_bf16_f32 v158, v158, v159
	v_cvt_pk_bf16_f32 v159, v178, v179
	v_cvt_pk_bf16_f32 v132, v132, v133
	v_cvt_pk_bf16_f32 v133, v134, v135
	v_lshl_add_u64 v[134:135], v[164:165], 0, s[18:19]
	global_store_dwordx4 v[164:165], v[156:159], off
	global_store_dwordx4 v[134:135], v[130:133], off
	s_waitcnt lgkmcnt(0)
	s_andn2_b64 vcc, exec, s[16:17]
	s_cbranch_vccnz .LBB0_216
	s_waitcnt vmcnt(8)
	v_mov_b64_e32 v[38:39], v[126:127]
	v_mov_b64_e32 v[2:3], v[122:123]
	v_mov_b64_e32 v[6:7], v[118:119]
	v_mov_b64_e32 v[10:11], v[114:115]
	v_mov_b64_e32 v[14:15], v[110:111]
	v_mov_b64_e32 v[18:19], v[106:107]
	v_mov_b64_e32 v[22:23], v[102:103]
	v_mov_b64_e32 v[26:27], v[98:99]
	v_mov_b64_e32 v[30:31], v[90:91]
	v_mov_b64_e32 v[34:35], v[94:95]
	v_mov_b64_e32 v[42:43], v[82:83]
	v_mov_b64_e32 v[46:47], v[86:87]
	v_mov_b64_e32 v[50:51], v[74:75]
	v_mov_b64_e32 v[54:55], v[78:79]
	v_mov_b64_e32 v[58:59], v[66:67]
	v_mov_b64_e32 v[62:63], v[70:71]
	v_mov_b64_e32 v[40:41], v[128:129]
	v_mov_b64_e32 v[4:5], v[124:125]
	v_mov_b64_e32 v[8:9], v[120:121]
	v_mov_b64_e32 v[12:13], v[116:117]
	v_mov_b64_e32 v[16:17], v[112:113]
	v_mov_b64_e32 v[20:21], v[108:109]
	v_mov_b64_e32 v[24:25], v[104:105]
	v_mov_b64_e32 v[28:29], v[100:101]
	v_mov_b64_e32 v[32:33], v[92:93]
	v_mov_b64_e32 v[36:37], v[96:97]
	v_mov_b64_e32 v[44:45], v[84:85]
	v_mov_b64_e32 v[48:49], v[88:89]
	v_mov_b64_e32 v[52:53], v[76:77]
	v_mov_b64_e32 v[56:57], v[80:81]
	v_mov_b64_e32 v[60:61], v[68:69]
	v_mov_b64_e32 v[64:65], v[72:73]
	v_mov_b64_e32 v[146:147], v[148:149]
	v_mov_b64_e32 v[142:143], v[150:151]
	s_mov_b32 s0, s33
	s_branch .LBB0_216

; #define LAS __attribute__((address_space(3)))
; #define TR_LOAD(p) __builtin_nontemporal_load(p)
; __device__ __forceinline__ TrItem tr_decode(int it, const float* const* in, unsigned char* ws, int lane) {
;     ...
;     const int rh = r >> 3, rl = r & 7, nq = ndb >> DL, kbh = rh / nq, dbh = rh - kbh * nq;
;     const int kb = (kbh << KL) + (rl >> DL), db = (dbh << DL) + (rl & ((1 << DL) - 1)), d0 = db * 64, k0 = kb * 64;
;     ...
;     const int kb = r / ndb, db = r - kb * ndb, d0 = db * 64, k0 = kb * 64;
;     ...
;     const int blk = d0 + 32 * ((lane & 15) >> 3);
;     const float* src = W; int s0 = blk;
;     if (kind == 1) { const int pn = blk >> 8, bj = (blk >> 7) & 1, o = blk & 127; src = bj ? W2 : W; s0 = pn * 128 + o; }
;     else if (kind == 2) s0 = win_src(blk);
;     TrItem t; t.src = src + (size_t)(k0 + (lane >> 4)) * N + s0 + 4 * (lane & 7); t.gain = gain ? gain + k0 + 8 * (lane & 7) : nullptr;
;     t.dst = WT + (size_t)(d0 + (lane >> 3)) * K + k0 + 8 * (lane & 7); t.N = N; t.K = K; t.nts = nts && TR_NTS;
;     if (woh) { t.dst = WT + ((size_t)((k0 >> 9) * 2048 + d0 + (lane >> 3))) * 512 + (k0 & 511) + 8 * (lane & 7); t.K = 512; }
;     return t;
; }
;     __device__ __forceinline__ int count() const { return (e0 - b0) + (e1 - b1) + (e2 - b2); }
; __device__ __forceinline__ void tr_all(const float* const* in, unsigned char* ws, LAS float* scr, int gw, int ngw, int lane, const TrRanges rg) {
;     const int TR_CNT = rg.count();
;     if (gw >= TR_CNT) return;
;     TrItem cur = tr_decode(rg.item(gw), in, ws, lane);
;     f32x4 v[16];
; #pragma unroll
;     for (int i = 0; i < 16; ++i) v[i] = TR_LOAD((const f32x4*)(cur.src + (size_t)(4 * i) * cur.N));
;     for (int it = gw; it < TR_CNT; it += ngw) {
;         const int nit = it + ngw; const bool hn = nit < TR_CNT;
;         TrItem nx = cur; f32x4 w[16];
;         if (hn) { nx = tr_decode(rg.item(nit), in, ws, lane);
; #pragma unroll
;             for (int i = 0; i < 16; ++i) w[i] = TR_LOAD((const f32x4*)(nx.src + (size_t)(4 * i) * nx.N)); }
.LBB0_274:
	v_cmp_ne_u64_e32 vcc, 0, v[144:145]
	v_mov_b32_e32 v192, 1.0
	v_mov_b32_e32 v193, 1.0
	v_mov_b32_e32 v194, 1.0
	v_mov_b32_e32 v195, 1.0
	v_mov_b32_e32 v196, 1.0
	v_mov_b32_e32 v197, 1.0
	v_mov_b32_e32 v198, 1.0
	v_mov_b32_e32 v199, 1.0
	s_and_saveexec_b64 s[100:101], vcc
	s_cbranch_execz .Ltr_g_i3
	global_load_dwordx4 v[192:195], v[144:145], off
	global_load_dwordx4 v[196:199], v[144:145], off offset:16
.Ltr_g_i3:
	s_or_b64 exec, exec, s[100:101]
	s_add_i32 s28, s4, s2
	s_cmpk_lt_i32 s28, 0x1600
	s_cselect_b64 s[16:17], -1, 0
	s_cmpk_gt_i32 s28, 0x15ff
	s_cselect_b64 s[14:15], -1, 0
	s_and_b64 vcc, exec, s[14:15]
	v_mov_b64_e32 v[150:151], v[140:141]
	v_mov_b64_e32 v[148:149], v[144:145]
	s_cbranch_vccnz .LBB0_276
	s_ashr_i32 s5, s28, 3
	s_mul_hi_i32 s18, s5, 0x2e8ba2e9
	s_lshr_b32 s19, s18, 31
	s_ashr_i32 s18, s18, 3
	s_add_i32 s18, s18, s19
	s_mul_i32 s19, s18, 0xffffd4
	s_add_i32 s19, s19, s5
	s_lshl_b32 s5, s18, 7
	s_and_b32 s18, s3, 64
	s_lshl_b32 s29, s19, 8
	s_and_b32 s30, s21, 0xc0
	s_or_b32 s18, s5, s18
	s_and_b32 s5, s21, 64
	s_bitcmp0_b32 s4, 1
	s_cselect_b32 s4, s75, s77
	s_cselect_b32 s19, s74, s76
	v_mov_b32_e32 v67, s4
	s_ashr_i32 s4, s29, 1
	s_or_b32 s4, s5, s4
	v_mov_b32_e32 v66, s19
	v_or_b32_e32 v68, s4, v152
	v_or_b32_e32 v69, s18, v153
	v_mad_i64_i32 v[66:67], s[4:5], v69, s20, v[66:67]
	v_ashrrev_i32_e32 v69, 31, v68
	v_lshl_add_u64 v[66:67], v[68:69], 2, v[66:67]
	v_lshl_add_u64 v[122:123], v[66:67], 0, v[138:139]
	v_add_co_u32_e32 v70, vcc, 0x16000, v122
	v_or_b32_e32 v130, s30, v154
	s_nop 0
	v_addc_co_u32_e32 v71, vcc, 0, v123, vcc
	v_add_co_u32_e32 v74, vcc, 0x2c000, v122
	global_load_dwordx4 v[66:69], v[122:123], off nt
	s_nop 0
	global_load_dwordx4 v[70:73], v[70:71], off nt
	v_addc_co_u32_e32 v75, vcc, 0, v123, vcc
	v_add_co_u32_e32 v78, vcc, 0x42000, v122
	v_or_b32_e32 v130, s29, v130
	s_nop 0
	v_addc_co_u32_e32 v79, vcc, 0, v123, vcc
	v_add_co_u32_e32 v82, vcc, 0x58000, v122
	global_load_dwordx4 v[74:77], v[74:75], off nt
	s_nop 0
	global_load_dwordx4 v[78:81], v[78:79], off nt
	v_addc_co_u32_e32 v83, vcc, 0, v123, vcc
	v_add_co_u32_e32 v86, vcc, 0x6e000, v122
	v_ashrrev_i32_e32 v131, 31, v130
	s_nop 0
	v_addc_co_u32_e32 v87, vcc, 0, v123, vcc
	v_add_co_u32_e32 v90, vcc, 0x84000, v122
	global_load_dwordx4 v[82:85], v[82:83], off nt
	s_nop 0
	global_load_dwordx4 v[86:89], v[86:87], off nt
	v_addc_co_u32_e32 v91, vcc, 0, v123, vcc
	v_add_co_u32_e32 v94, vcc, 0x9a000, v122
	v_lshlrev_b64 v[130:131], 12, v[130:131]
	s_nop 0
	v_addc_co_u32_e32 v95, vcc, 0, v123, vcc
	v_add_co_u32_e32 v98, vcc, 0xb0000, v122
	global_load_dwordx4 v[90:93], v[90:91], off nt
	s_nop 0
	global_load_dwordx4 v[94:97], v[94:95], off nt
	v_addc_co_u32_e32 v99, vcc, 0, v123, vcc
	v_add_co_u32_e32 v102, vcc, 0xc6000, v122
	s_ashr_i32 s19, s18, 31
	s_nop 0
	v_addc_co_u32_e32 v103, vcc, 0, v123, vcc
	v_add_co_u32_e32 v106, vcc, 0xdc000, v122
	global_load_dwordx4 v[98:101], v[98:99], off nt
	s_nop 0
	global_load_dwordx4 v[102:105], v[102:103], off nt
	v_addc_co_u32_e32 v107, vcc, 0, v123, vcc
	v_add_co_u32_e32 v110, vcc, 0xf2000, v122
	v_lshl_add_u64 v[130:131], s[12:13], 0, v[130:131]
	s_nop 0
	v_addc_co_u32_e32 v111, vcc, 0, v123, vcc
	v_add_co_u32_e32 v114, vcc, 0x108000, v122
	global_load_dwordx4 v[106:109], v[106:107], off nt
	s_nop 0
	global_load_dwordx4 v[110:113], v[110:111], off nt
	v_addc_co_u32_e32 v115, vcc, 0, v123, vcc
	v_add_co_u32_e32 v118, vcc, 0x11e000, v122
	v_lshl_add_u64 v[130:131], s[18:19], 1, v[130:131]
	s_nop 0
	v_addc_co_u32_e32 v119, vcc, 0, v123, vcc
	v_add_co_u32_e32 v124, vcc, 0x134000, v122
	global_load_dwordx4 v[114:117], v[114:115], off nt
	s_nop 0
	global_load_dwordx4 v[118:121], v[118:119], off nt
	v_addc_co_u32_e32 v125, vcc, 0, v123, vcc
	v_add_co_u32_e32 v126, vcc, 0x14a000, v122
	v_lshl_add_u64 v[132:133], s[18:19], 2, v[142:143]
	s_nop 0
	v_addc_co_u32_e32 v127, vcc, 0, v123, vcc
	global_load_dwordx4 v[122:125], v[124:125], off nt
	s_nop 0
	global_load_dwordx4 v[126:129], v[126:127], off nt
	v_mov_b32_e32 v147, v139
	v_cndmask_b32_e64 v149, v133, 0, s[0:1]
	v_cndmask_b32_e64 v148, v132, 0, s[0:1]
	v_lshl_add_u64 v[150:151], v[130:131], 0, v[146:147]
	s_waitcnt vmcnt(16)
	s_branch .Ltr_w_i3

; #define LAS __attribute__((address_space(3)))
; __device__ __forceinline__ unsigned cvtpk(float lo, float hi) { f32x2_t v = {lo, hi}; bf16x2_t b = __builtin_convertvector(v, bf16x2_t); return __builtin_bit_cast(unsigned, b); }
; __device__ __forceinline__ void tr_all(const float* const* in, unsigned char* ws, LAS float* scr, int gw, int ngw, int lane, const TrRanges rg) {
;     ...
;         LAS float* wp = scr + (lane >> 4) * 65 + 4 * (lane & 15);
; #pragma unroll
;         for (int i = 0; i < 16; ++i) { wp[(4 * i) * 65 + 0] = v[i][0]; wp[(4 * i) * 65 + 1] = v[i][1]; wp[(4 * i) * 65 + 2] = v[i][2]; wp[(4 * i) * 65 + 3] = v[i][3]; }
;         f32x4 g0 = {1.f, 1.f, 1.f, 1.f}, g1 = {1.f, 1.f, 1.f, 1.f};
;         if (cur.gain) { g0 = *(const f32x4*)cur.gain; g1 = *(const f32x4*)(cur.gain + 4); }
;         asm volatile("s_waitcnt lgkmcnt(0)" ::: "memory");
;         const LAS float* rp = scr + (8 * (lane & 7)) * 65 + (lane >> 3);
; #pragma unroll
;         for (int j = 0; j < 8; ++j) { const LAS float* s = rp + 8 * j;
;             u32x4 o; o.x = cvtpk(s[0 * 65] * g0[0], s[1 * 65] * g0[1]); o.y = cvtpk(s[2 * 65] * g0[2], s[3 * 65] * g0[3]);
;             o.z = cvtpk(s[4 * 65] * g1[0], s[5 * 65] * g1[1]); o.w = cvtpk(s[6 * 65] * g1[2], s[7 * 65] * g1[3]);
;             if (cur.nts) __builtin_nontemporal_store(o, (u32x4*)(cur.dst + (size_t)(8 * j) * cur.K)); else *(u32x4*)(cur.dst + (size_t)(8 * j) * cur.K) = o; }
.Ltr_w_i3:
	v_add_u32_e32 v130, 0x410, v155
	ds_write2_b32 v155, v62, v63 offset1:1
	ds_write2_b32 v155, v64, v65 offset0:2 offset1:3
	ds_write2_b32 v130, v58, v59 offset1:1
	v_add_u32_e32 v130, 0x418, v155
	ds_write2_b32 v130, v60, v61 offset1:1
	v_add_u32_e32 v130, 0x820, v155
	ds_write2_b32 v130, v54, v55 offset1:1
	v_add_u32_e32 v130, 0x828, v155
	ds_write2_b32 v130, v56, v57 offset1:1
	v_add_u32_e32 v130, 0xc30, v155
	ds_write2_b32 v130, v46, v47 offset1:1
	v_add_u32_e32 v130, 0xc38, v155
	ds_write2_b32 v130, v48, v49 offset1:1
	v_add_u32_e32 v130, 0x1040, v155
	ds_write2_b32 v130, v42, v43 offset1:1
	v_add_u32_e32 v130, 0x1048, v155
	ds_write2_b32 v130, v44, v45 offset1:1
	v_add_u32_e32 v130, 0x1450, v155
	ds_write2_b32 v130, v38, v39 offset1:1
	v_add_u32_e32 v130, 0x1458, v155
	ds_write2_b32 v130, v40, v41 offset1:1
	v_add_u32_e32 v130, 0x1860, v155
	ds_write2_b32 v130, v34, v35 offset1:1
	v_add_u32_e32 v130, 0x1868, v155
	ds_write2_b32 v130, v36, v37 offset1:1
	v_add_u32_e32 v130, 0x1c70, v155
	ds_write2_b32 v130, v30, v31 offset1:1
	v_add_u32_e32 v130, 0x1c78, v155
	ds_write2_b32 v130, v32, v33 offset1:1
	v_add_u32_e32 v130, 0x2080, v155
	ds_write2_b32 v130, v26, v27 offset1:1
	v_add_u32_e32 v130, 0x2088, v155
	ds_write2_b32 v130, v28, v29 offset1:1
	v_add_u32_e32 v130, 0x2490, v155
	ds_write2_b32 v130, v22, v23 offset1:1
	v_add_u32_e32 v130, 0x2498, v155
	ds_write2_b32 v130, v24, v25 offset1:1
	v_add_u32_e32 v130, 0x28a0, v155
	ds_write2_b32 v130, v18, v19 offset1:1
	v_add_u32_e32 v130, 0x28a8, v155
	ds_write2_b32 v130, v20, v21 offset1:1
	v_add_u32_e32 v130, 0x2cb0, v155
	ds_write2_b32 v130, v14, v15 offset1:1
	v_add_u32_e32 v130, 0x2cb8, v155
	ds_write2_b32 v130, v16, v17 offset1:1
	v_add_u32_e32 v130, 0x30c0, v155
	ds_write2_b32 v130, v10, v11 offset1:1
	v_add_u32_e32 v130, 0x30c8, v155
	ds_write2_b32 v130, v12, v13 offset1:1
	v_add_u32_e32 v130, 0x34d0, v155
	ds_write2_b32 v130, v6, v7 offset1:1
	v_add_u32_e32 v130, 0x34d8, v155
	ds_write2_b32 v130, v8, v9 offset1:1
	v_add_u32_e32 v130, 0x38e0, v155
	ds_write2_b32 v130, v2, v3 offset1:1
	v_add_u32_e32 v130, 0x38e8, v155
	ds_write2_b32 v130, v4, v5 offset1:1
	v_add_u32_e32 v130, 0x3cf0, v155
	ds_write2_b32 v130, v50, v51 offset1:1
	v_add_u32_e32 v130, 0x3cf8, v155
	ds_write2_b32 v130, v52, v53 offset1:1
.LBB0_278:
	s_waitcnt lgkmcnt(0)
	ds_read2_b32 v[162:163], v156 offset1:8
	ds_read2_b32 v[164:165], v156 offset0:65 offset1:73
	ds_read2_b32 v[166:167], v156 offset0:130 offset1:138
	ds_read2_b32 v[168:169], v156 offset0:195 offset1:203
	v_add_u32_e32 v147, 0x400, v156
	ds_read2_b32 v[170:171], v147 offset0:4 offset1:12
	ds_read2_b32 v[172:173], v147 offset0:69 offset1:77
	ds_read2_b32 v[174:175], v147 offset0:134 offset1:142
	ds_read2_b32 v[176:177], v147 offset0:199 offset1:207
	s_waitcnt lgkmcnt(7)
	v_mov_b32_e32 v158, v162
	s_waitcnt lgkmcnt(6)
	v_mov_b32_e32 v159, v164
	s_waitcnt lgkmcnt(5)
	v_mov_b32_e32 v160, v166
	s_waitcnt lgkmcnt(4)
	v_mov_b32_e32 v161, v168
	v_pk_mul_f32 v[158:159], v[192:193], v[158:159]
	v_pk_mul_f32 v[160:161], v[194:195], v[160:161]
	v_cvt_pk_bf16_f32 v158, v158, v159
	v_cvt_pk_bf16_f32 v159, v160, v161
	s_waitcnt lgkmcnt(3)
	v_mov_b32_e32 v160, v170
	s_waitcnt lgkmcnt(2)
	v_mov_b32_e32 v161, v172
	s_waitcnt lgkmcnt(1)
	v_mov_b32_e32 v178, v174
	s_waitcnt lgkmcnt(0)
	v_mov_b32_e32 v179, v176
	v_pk_mul_f32 v[160:161], v[196:197], v[160:161]
	v_pk_mul_f32 v[178:179], v[198:199], v[178:179]
	v_cvt_pk_bf16_f32 v160, v160, v161
	v_cvt_pk_bf16_f32 v161, v178, v179
	v_mov_b32_e32 v164, v163
	v_mov_b32_e32 v168, v167
	global_store_dwordx4 v[140:141], v[158:161], off
	v_mov_b32_e32 v172, v171
	v_mov_b32_e32 v176, v175
	v_pk_mul_f32 v[158:159], v[192:193], v[164:165]
	v_pk_mul_f32 v[160:161], v[194:195], v[168:169]
	v_cvt_pk_bf16_f32 v158, v158, v159
	v_cvt_pk_bf16_f32 v159, v160, v161
	v_pk_mul_f32 v[160:161], v[196:197], v[172:173]
	v_pk_mul_f32 v[162:163], v[198:199], v[176:177]
	v_add_co_u32_e32 v166, vcc, s22, v140
	v_cvt_pk_bf16_f32 v160, v160, v161
	v_cvt_pk_bf16_f32 v161, v162, v163
	v_addc_co_u32_e32 v167, vcc, 0, v141, vcc
	ds_read2_b32 v[162:163], v156 offset0:81 offset1:89
	ds_read2_b32 v[164:165], v156 offset0:16 offset1:24
	global_store_dwordx4 v[166:167], v[158:161], off
	ds_read2_b32 v[166:167], v156 offset0:146 offset1:154
	ds_read2_b32 v[168:169], v156 offset0:211 offset1:219
	ds_read2_b32 v[170:171], v147 offset0:20 offset1:28
	ds_read2_b32 v[172:173], v147 offset0:85 offset1:93
	ds_read2_b32 v[174:175], v147 offset0:150 offset1:158
	ds_read2_b32 v[176:177], v147 offset0:215 offset1:223
	s_waitcnt lgkmcnt(6)
	v_mov_b32_e32 v158, v164
	v_mov_b32_e32 v159, v162
	s_waitcnt lgkmcnt(5)
	v_mov_b32_e32 v160, v166
	s_waitcnt lgkmcnt(4)
	v_mov_b32_e32 v161, v168
	v_pk_mul_f32 v[158:159], v[192:193], v[158:159]
	v_pk_mul_f32 v[160:161], v[194:195], v[160:161]
	v_cvt_pk_bf16_f32 v158, v158, v159
	v_cvt_pk_bf16_f32 v159, v160, v161
	s_waitcnt lgkmcnt(3)
	v_mov_b32_e32 v160, v170
	s_waitcnt lgkmcnt(2)
	v_mov_b32_e32 v161, v172
	s_waitcnt lgkmcnt(1)
	v_mov_b32_e32 v178, v174
	s_waitcnt lgkmcnt(0)
; #define LAS __attribute__((address_space(3)))
; __device__ __forceinline__ unsigned cvtpk(float lo, float hi) { f32x2_t v = {lo, hi}; bf16x2_t b = __builtin_convertvector(v, bf16x2_t); return __builtin_bit_cast(unsigned, b); }
; __device__ __forceinline__ void tr_all(const float* const* in, unsigned char* ws, LAS float* scr, int gw, int ngw, int lane, const TrRanges rg) {
;     ...
;         for (int j = 0; j < 8; ++j) { const LAS float* s = rp + 8 * j;
;             u32x4 o; o.x = cvtpk(s[0 * 65] * g0[0], s[1 * 65] * g0[1]); o.y = cvtpk(s[2 * 65] * g0[2], s[3 * 65] * g0[3]);
;             o.z = cvtpk(s[4 * 65] * g1[0], s[5 * 65] * g1[1]); o.w = cvtpk(s[6 * 65] * g1[2], s[7 * 65] * g1[3]);
;             if (cur.nts) __builtin_nontemporal_store(o, (u32x4*)(cur.dst + (size_t)(8 * j) * cur.K)); else *(u32x4*)(cur.dst + (size_t)(8 * j) * cur.K) = o; }
;         asm volatile("s_waitcnt lgkmcnt(0)" ::: "memory");
;         if (hn) {
; #pragma unroll
;             for (int i = 0; i < 16; ++i) v[i] = w[i];
;             cur = nx; }
	v_mov_b32_e32 v179, v176
	v_pk_mul_f32 v[160:161], v[196:197], v[160:161]
	v_pk_mul_f32 v[178:179], v[198:199], v[178:179]
	v_cvt_pk_bf16_f32 v160, v160, v161
	v_cvt_pk_bf16_f32 v161, v178, v179
	v_add_co_u32_e32 v178, vcc, s23, v140
	v_mov_b32_e32 v162, v165
	s_nop 0
	v_addc_co_u32_e32 v179, vcc, 0, v141, vcc
	v_mov_b32_e32 v168, v167
	global_store_dwordx4 v[178:179], v[158:161], off
	v_mov_b32_e32 v172, v171
	v_mov_b32_e32 v176, v175
	v_pk_mul_f32 v[158:159], v[192:193], v[162:163]
	v_pk_mul_f32 v[160:161], v[194:195], v[168:169]
	v_cvt_pk_bf16_f32 v158, v158, v159
	v_cvt_pk_bf16_f32 v159, v160, v161
	v_pk_mul_f32 v[160:161], v[196:197], v[172:173]
	v_pk_mul_f32 v[162:163], v[198:199], v[176:177]
	v_add_co_u32_e32 v166, vcc, s24, v140
	v_cvt_pk_bf16_f32 v160, v160, v161
	v_cvt_pk_bf16_f32 v161, v162, v163
	v_addc_co_u32_e32 v167, vcc, 0, v141, vcc
	ds_read2_b32 v[162:163], v156 offset0:97 offset1:105
	ds_read2_b32 v[164:165], v156 offset0:32 offset1:40
	global_store_dwordx4 v[166:167], v[158:161], off
	ds_read2_b32 v[166:167], v156 offset0:162 offset1:170
	ds_read2_b32 v[168:169], v156 offset0:227 offset1:235
	ds_read2_b32 v[170:171], v147 offset0:36 offset1:44
	ds_read2_b32 v[172:173], v147 offset0:101 offset1:109
	ds_read2_b32 v[174:175], v147 offset0:166 offset1:174
	ds_read2_b32 v[176:177], v147 offset0:231 offset1:239
	s_waitcnt lgkmcnt(6)
	v_mov_b32_e32 v158, v164
	v_mov_b32_e32 v159, v162
	s_waitcnt lgkmcnt(5)
	v_mov_b32_e32 v160, v166
	s_waitcnt lgkmcnt(4)
	v_mov_b32_e32 v161, v168
	v_pk_mul_f32 v[158:159], v[192:193], v[158:159]
	v_pk_mul_f32 v[160:161], v[194:195], v[160:161]
	v_cvt_pk_bf16_f32 v158, v158, v159
	v_cvt_pk_bf16_f32 v159, v160, v161
	s_waitcnt lgkmcnt(3)
	v_mov_b32_e32 v160, v170
	s_waitcnt lgkmcnt(2)
	v_mov_b32_e32 v161, v172
	s_waitcnt lgkmcnt(1)
	v_mov_b32_e32 v178, v174
	s_waitcnt lgkmcnt(0)
	v_mov_b32_e32 v179, v176
	v_pk_mul_f32 v[160:161], v[196:197], v[160:161]
	v_pk_mul_f32 v[178:179], v[198:199], v[178:179]
	v_cvt_pk_bf16_f32 v160, v160, v161
	v_cvt_pk_bf16_f32 v161, v178, v179
	v_add_co_u32_e32 v178, vcc, s25, v140
	v_mov_b32_e32 v162, v165
	s_nop 0
	v_addc_co_u32_e32 v179, vcc, 0, v141, vcc
	v_mov_b32_e32 v168, v167
	global_store_dwordx4 v[178:179], v[158:161], off
	v_mov_b32_e32 v172, v171
	v_mov_b32_e32 v176, v175
	v_pk_mul_f32 v[158:159], v[192:193], v[162:163]
	v_pk_mul_f32 v[160:161], v[194:195], v[168:169]
	v_cvt_pk_bf16_f32 v158, v158, v159
	v_cvt_pk_bf16_f32 v159, v160, v161
	v_pk_mul_f32 v[160:161], v[196:197], v[172:173]
	v_pk_mul_f32 v[162:163], v[198:199], v[176:177]
	v_add_co_u32_e32 v166, vcc, s26, v140
	v_cvt_pk_bf16_f32 v160, v160, v161
	v_cvt_pk_bf16_f32 v161, v162, v163
	v_addc_co_u32_e32 v167, vcc, 0, v141, vcc
	ds_read2_b32 v[162:163], v156 offset0:113 offset1:121
	ds_read2_b32 v[164:165], v156 offset0:48 offset1:56
	global_store_dwordx4 v[166:167], v[158:161], off
	ds_read2_b32 v[166:167], v156 offset0:178 offset1:186
	ds_read2_b32 v[168:169], v156 offset0:243 offset1:251
	ds_read2_b32 v[170:171], v147 offset0:52 offset1:60
	ds_read2_b32 v[172:173], v147 offset0:117 offset1:125
	ds_read2_b32 v[174:175], v147 offset0:182 offset1:190
	ds_read2_b32 v[176:177], v147 offset0:247 offset1:255
	s_waitcnt lgkmcnt(6)
	v_mov_b32_e32 v158, v164
	v_mov_b32_e32 v159, v162
	s_waitcnt lgkmcnt(5)
	v_mov_b32_e32 v160, v166
	s_waitcnt lgkmcnt(4)
	v_mov_b32_e32 v161, v168
	v_pk_mul_f32 v[158:159], v[192:193], v[158:159]
	v_pk_mul_f32 v[160:161], v[194:195], v[160:161]
	v_cvt_pk_bf16_f32 v158, v158, v159
	v_cvt_pk_bf16_f32 v159, v160, v161
	s_waitcnt lgkmcnt(3)
	v_mov_b32_e32 v160, v170
	s_waitcnt lgkmcnt(2)
	v_mov_b32_e32 v161, v172
	s_waitcnt lgkmcnt(1)
	v_mov_b32_e32 v178, v174
	s_waitcnt lgkmcnt(0)
	v_mov_b32_e32 v179, v176
	v_pk_mul_f32 v[160:161], v[196:197], v[160:161]
	v_pk_mul_f32 v[178:179], v[198:199], v[178:179]
	v_mov_b32_e32 v162, v165
	v_mov_b32_e32 v168, v167
	v_cvt_pk_bf16_f32 v160, v160, v161
	v_cvt_pk_bf16_f32 v161, v178, v179
	v_add_co_u32_e32 v178, vcc, s27, v140
	v_pk_mul_f32 v[130:131], v[192:193], v[162:163]
	v_pk_mul_f32 v[132:133], v[194:195], v[168:169]
	v_mov_b32_e32 v172, v171
	v_mov_b32_e32 v176, v175
	v_addc_co_u32_e32 v179, vcc, 0, v141, vcc
	v_cvt_pk_bf16_f32 v130, v130, v131
	v_cvt_pk_bf16_f32 v131, v132, v133
	v_pk_mul_f32 v[132:133], v[196:197], v[172:173]
	v_pk_mul_f32 v[134:135], v[198:199], v[176:177]
	v_cvt_pk_bf16_f32 v132, v132, v133
	v_cvt_pk_bf16_f32 v133, v134, v135
	v_add_co_u32_e32 v134, vcc, 0x38000, v140
	global_store_dwordx4 v[178:179], v[158:161], off
	s_nop 0
	v_addc_co_u32_e32 v135, vcc, 0, v141, vcc
	global_store_dwordx4 v[134:135], v[130:133], off
	s_waitcnt lgkmcnt(0)
	s_andn2_b64 vcc, exec, s[16:17]
	s_cbranch_vccnz .LBB0_273
	s_waitcnt vmcnt(8)
	v_mov_b64_e32 v[50:51], v[126:127]
	v_mov_b64_e32 v[2:3], v[122:123]
	v_mov_b64_e32 v[6:7], v[118:119]
	v_mov_b64_e32 v[10:11], v[114:115]
	v_mov_b64_e32 v[14:15], v[110:111]
	v_mov_b64_e32 v[18:19], v[106:107]
	v_mov_b64_e32 v[22:23], v[102:103]
	v_mov_b64_e32 v[26:27], v[98:99]
	v_mov_b64_e32 v[30:31], v[94:95]
	v_mov_b64_e32 v[34:35], v[90:91]
	v_mov_b64_e32 v[38:39], v[86:87]
	v_mov_b64_e32 v[42:43], v[82:83]
	v_mov_b64_e32 v[46:47], v[78:79]
	v_mov_b64_e32 v[54:55], v[74:75]
	v_mov_b64_e32 v[58:59], v[70:71]
	v_mov_b64_e32 v[62:63], v[66:67]
	v_mov_b64_e32 v[52:53], v[128:129]
	v_mov_b64_e32 v[4:5], v[124:125]
	v_mov_b64_e32 v[8:9], v[120:121]
	v_mov_b64_e32 v[12:13], v[116:117]
	v_mov_b64_e32 v[16:17], v[112:113]
	v_mov_b64_e32 v[20:21], v[108:109]
	v_mov_b64_e32 v[24:25], v[104:105]
	v_mov_b64_e32 v[28:29], v[100:101]
	v_mov_b64_e32 v[32:33], v[96:97]
	v_mov_b64_e32 v[36:37], v[92:93]
	v_mov_b64_e32 v[40:41], v[88:89]
	v_mov_b64_e32 v[44:45], v[84:85]
	v_mov_b64_e32 v[48:49], v[80:81]
	v_mov_b64_e32 v[56:57], v[76:77]
	v_mov_b64_e32 v[60:61], v[72:73]
	v_mov_b64_e32 v[64:65], v[68:69]
	v_mov_b64_e32 v[144:145], v[148:149]
	v_mov_b64_e32 v[140:141], v[150:151]
	s_branch .LBB0_273
